# v55 + helper-wave load addresses computed on the SALU (saddr loads, per-unit constant VGPR offsets) instead of 13 VALU per chunk
# baseline (speedup 1.0000x reference)
.LBB0_721:
	s_and_b64 s[8:9], s[0:1], exec
	v_readlane_b32 s8, v255, 9
	v_and_b32_e32 v166, 63, v44
	v_readlane_b32 s9, v255, 10
	v_and_b32_e32 v26, 31, v44
	v_lshlrev_b32_e32 v27, 6, v44
	s_cselect_b32 s27, s72, s9
	s_cselect_b32 s26, s39, s8
	s_mov_b64 s[8:9], -1
	s_cmp_lt_i32 s20, 4
	v_lshl_add_u32 v118, v45, 4, 0
	v_lshl_or_b32 v164, s42, 6, v166
	v_and_b32_e32 v119, 0x600, v27
	v_and_b32_e32 v123, 0x100, v27
	v_and_b32_e32 v129, 0xc0, v27
	v_lshlrev_b32_e32 v116, 2, v26
	s_waitcnt lgkmcnt(0)
	s_barrier
	s_cbranch_scc1 .LBB0_831
	v_lshl_or_b32 v167, s42, 2, v165
	s_mul_i32 s8, s42, 0x2100
	v_mov_b32_e32 v121, s7
	v_or_b32_e32 v120, s6, v46
	v_mad_u64_u32 v[124:125], s[6:7], v167, s69, v[118:119]
	s_add_i32 s8, s8, 0
	s_ashr_i32 s23, s22, 31
	v_lshlrev_b32_e32 v26, 2, v44
	v_lshrrev_b32_e32 v125, 5, v164
	s_add_i32 s15, s8, 0x1b000
	v_and_b32_e32 v122, 28, v26
	v_lshlrev_b32_e32 v26, 11, v125
	s_lshl_b64 s[42:43], s[22:23], 2
	v_add3_u32 v27, s70, v26, v119
	s_add_u32 s42, s26, s42
	v_add3_u32 v168, v27, v123, v129
	s_addc_u32 s43, s27, s43
	v_mov_b32_e32 v117, v115
	v_add_u32_e32 v27, 0x100, v164
	v_lshl_add_u64 v[126:127], s[42:43], 0, v[116:117]
	v_lshrrev_b32_e32 v117, 5, v27
	v_lshlrev_b32_e32 v27, 11, v117
	s_ashr_i32 s37, s36, 31
	v_add3_u32 v26, 0, v26, v119
	s_lshl_b64 s[36:37], s[36:37], 2
	v_add3_u32 v173, v26, v123, v129
	v_add3_u32 v26, 0, v27, v119
	s_add_u32 s36, s40, s36
	v_add3_u32 v174, v26, v123, v129
	v_lshlrev_b32_e32 v232, 2, v44
	v_and_b32_e32 v232, 48, v232
	v_xor_b32_e32 v233, 16, v232
	v_xor_b32_e32 v234, 32, v232
	v_xor_b32_e32 v235, 48, v232
	v_add_u32_e32 v224, v173, v232
	v_add_u32_e32 v225, v173, v233
	v_add_u32_e32 v226, v173, v234
	v_add_u32_e32 v227, v173, v235
	v_add_u32_e32 v228, 0x8000, v224
	v_add_u32_e32 v229, 0x8000, v225
	v_add_u32_e32 v230, 0x8000, v226
	v_add_u32_e32 v231, 0x8000, v227
	v_lshlrev_b32_e32 v26, 3, v44
	s_addc_u32 s37, s41, s37
	v_lshrrev_b32_e32 v171, 3, v166
	v_and_b32_e32 v128, 56, v26
	s_lshl_b64 s[40:41], s[22:23], 1
	v_add3_u32 v28, s70, v27, v119
	v_mul_u32_u24_e32 v26, 0x84, v128
	v_lshlrev_b32_e32 v27, 2, v171
	s_add_u32 s40, s16, s40
	v_lshl_add_u32 v176, v122, 2, s15
	v_add3_u32 v182, s15, v26, v27
	s_addc_u32 s41, s17, s41
	s_lshl_b32 s15, s20, 6
	v_or_b32_e32 v26, s15, v166
	s_addk_i32 s15, 0xff00
	v_add3_u32 v169, v28, v123, v129
	v_lshlrev_b32_e32 v28, 7, v167
	v_lshlrev_b32_e32 v114, 1, v122
	v_lshrrev_b32_e32 v183, 5, v26
	v_or_b32_e32 v26, s15, v166
	v_cmp_gt_u32_e64 s[6:7], 8, v45
	s_mov_b32 s45, 0
	v_cmp_eq_u32_e64 s[8:9], 0, v45
	v_add_u32_e32 v170, 64, v167
	v_add_u32_e32 v172, 0x50, v167
	v_add_u32_e32 v175, 0x60, v167
	v_add_u32_e32 v177, 0x70, v167
	v_mul_u32_u24_e32 v178, 0x84, v171
	v_or_b32_e32 v179, 8, v171
	v_or_b32_e32 v180, 16, v171
	v_or_b32_e32 v181, 24, v171
	v_lshl_add_u64 v[130:131], s[40:41], 0, v[114:115]
	v_lshrrev_b32_e32 v184, 5, v26
	v_lshl_or_b32 v185, s20, 2, v165
	s_mov_b32 s23, -4
	v_add_u32_e32 v186, v118, v28
	s_mov_b32 s49, s11
	s_mov_b32 s46, 0
	s_mov_b64 s[58:59], s[40:41]
	s_bitcmp1_b32 s10, 1
	s_cselect_b32 s56, -1, 1
	s_cselect_b32 s57, 0x1ff0, 0
	s_cselect_b32 s63, 15, 0
	v_mov_b32_e32 v239, s63
	v_mad_i32_i24 v239, v167, s56, v239
	v_lshlrev_b32_e32 v236, 12, v239
	v_lshl_add_u32 v236, v120, 1, v236
	v_lshlrev_b32_e32 v237, 1, v236
	v_lshl_add_u32 v238, v239, 12, v114
	s_branch .LBB0_726

.LBB0_726:
	s_add_i32 s23, s23, 4
	s_min_u32 s47, s23, 0x1fb
	s_lshl_b32 s60, s47, 4
	s_addk_i32 s60, 0x40
	s_mul_i32 s60, s60, s56
	s_add_i32 s60, s60, s57
	s_lshl_b32 s61, s60, 12
	s_lshl_b32 s62, s60, 13
	s_add_u32 s64, s12, s61
	s_addc_u32 s65, s13, 0
	global_load_dwordx2 v[160:161], v236, s[64:65]
	s_add_u32 s64, s18, s61
	s_addc_u32 s65, s19, 0
	global_load_dwordx2 v[162:163], v236, s[64:65]
	s_add_u32 s64, s94, s61
	s_addc_u32 s65, s95, 0
	global_load_dwordx2 v[158:159], v236, s[64:65]
	s_add_u32 s64, s28, s62
	s_addc_u32 s65, s29, 0
	global_load_dwordx4 v[102:105], v237, s[64:65]
	s_add_u32 s64, s58, s61
	s_addc_u32 s65, s59, 0
	global_load_dwordx2 v[156:157], v238, s[64:65]
	s_waitcnt vmcnt(18)
	v_pk_add_f32 v[110:111], v[12:13], -1.0 op_sel_hi:[1,0]
	s_add_u32 s64, s30, s62
	s_addc_u32 s65, s31, 0
	global_load_dwordx4 v[98:101], v237, s[64:65]
	v_pk_add_f32 v[112:113], v[10:11], -1.0 op_sel_hi:[1,0]
	v_lshlrev_b32_e32 v188, 16, v142
	v_and_b32_e32 v189, 0xffff0000, v142
	v_lshlrev_b32_e32 v190, 16, v143
	v_and_b32_e32 v191, 0xffff0000, v143
	v_lshlrev_b32_e32 v106, 16, v140
	v_and_b32_e32 v107, 0xffff0000, v140
	v_lshlrev_b32_e32 v108, 16, v141
	v_and_b32_e32 v109, 0xffff0000, v141
	v_pk_fma_f32 v[110:111], v[8:9], v[110:111], 1.0 op_sel_hi:[1,1,0]
	v_pk_fma_f32 v[112:113], v[6:7], v[112:113], 1.0 op_sel_hi:[1,1,0]
	v_pk_mul_f32 v[108:109], v[110:111], v[108:109]
	v_pk_mul_f32 v[106:107], v[112:113], v[106:107]
	v_lshlrev_b32_e32 v110, 16, v134
	v_and_b32_e32 v111, 0xffff0000, v134
	v_lshlrev_b32_e32 v112, 16, v135
	v_and_b32_e32 v113, 0xffff0000, v135
	v_xor_b32_e32 v143, 0x80000000, v191
	v_xor_b32_e32 v142, 0x80000000, v190
	v_xor_b32_e32 v141, 0x80000000, v189
	v_xor_b32_e32 v140, 0x80000000, v188
	v_pk_mul_f32 v[12:13], v[12:13], v[190:191]
	v_pk_mul_f32 v[10:11], v[10:11], v[188:189]
	ds_write_b128 v124, v[140:143] offset:20480
	ds_write_b128 v124, v[14:17] offset:20736
	ds_write_b128 v124, v[10:13] offset:20992
	ds_write_b128 v124, v[106:109] offset:21248
	ds_write_b128 v124, v[110:113] offset:21504
	s_and_saveexec_b64 s[40:41], s[6:7]
	s_cbranch_execz .LBB0_732
	s_waitcnt vmcnt(18)
	v_lshlrev_b32_e32 v10, 16, v136
	v_and_b32_e32 v11, 0xffff0000, v136
	v_lshlrev_b32_e32 v12, 16, v137
	v_and_b32_e32 v13, 0xffff0000, v137
	ds_write_b128 v186, v[10:13] offset:43008

.LBB0_752:
	s_waitcnt lgkmcnt(0)
	s_barrier
	s_min_u32 s15, s23, 0x1fa
	s_lshl_b32 s60, s15, 4
	s_addk_i32 s60, 0x50
	s_mul_i32 s60, s60, s56
	s_add_i32 s60, s60, s57
	s_lshl_b32 s61, s60, 12
	s_lshl_b32 s62, s60, 13
	s_add_u32 s64, s12, s61
	s_addc_u32 s65, s13, 0
	global_load_dwordx2 v[140:141], v236, s[64:65]
	s_add_u32 s64, s18, s61
	s_addc_u32 s65, s19, 0
	global_load_dwordx2 v[142:143], v236, s[64:65]
	s_add_u32 s64, s94, s61
	s_addc_u32 s65, s95, 0
	global_load_dwordx2 v[134:135], v236, s[64:65]
	s_add_u32 s64, s28, s62
	s_addc_u32 s65, s29, 0
	global_load_dwordx4 v[14:17], v237, s[64:65]
	s_add_u32 s64, s58, s61
	s_addc_u32 s65, s59, 0
	global_load_dwordx2 v[136:137], v238, s[64:65]
	s_waitcnt vmcnt(19)
	v_pk_add_f32 v[110:111], v[20:21], -1.0 op_sel_hi:[1,0]
	s_add_u32 s64, s30, s62
	s_addc_u32 s65, s31, 0
	global_load_dwordx4 v[10:13], v237, s[64:65]
	v_pk_add_f32 v[112:113], v[18:19], -1.0 op_sel_hi:[1,0]
	v_lshlrev_b32_e32 v188, 16, v146
	v_and_b32_e32 v189, 0xffff0000, v146
	v_lshlrev_b32_e32 v190, 16, v147
	v_and_b32_e32 v191, 0xffff0000, v147
	v_lshlrev_b32_e32 v106, 16, v144
	v_and_b32_e32 v107, 0xffff0000, v144
	v_lshlrev_b32_e32 v108, 16, v145
	v_and_b32_e32 v109, 0xffff0000, v145
	v_pk_fma_f32 v[110:111], v[8:9], v[110:111], 1.0 op_sel_hi:[1,1,0]
	v_pk_fma_f32 v[112:113], v[6:7], v[112:113], 1.0 op_sel_hi:[1,1,0]
	v_pk_mul_f32 v[108:109], v[110:111], v[108:109]
	v_pk_mul_f32 v[106:107], v[112:113], v[106:107]
	v_lshlrev_b32_e32 v110, 16, v138
	v_and_b32_e32 v111, 0xffff0000, v138
	v_lshlrev_b32_e32 v112, 16, v139
	v_and_b32_e32 v113, 0xffff0000, v139
	v_xor_b32_e32 v147, 0x80000000, v191
	v_xor_b32_e32 v146, 0x80000000, v190
	v_xor_b32_e32 v145, 0x80000000, v189
	v_xor_b32_e32 v144, 0x80000000, v188
	v_pk_mul_f32 v[20:21], v[20:21], v[190:191]
	v_pk_mul_f32 v[18:19], v[18:19], v[188:189]
	ds_write_b128 v124, v[144:147]
	ds_write_b128 v124, v[22:25] offset:256
	ds_write_b128 v124, v[18:21] offset:512
	ds_write_b128 v124, v[106:109] offset:768
	ds_write_b128 v124, v[110:113] offset:1024
	s_and_saveexec_b64 s[40:41], s[6:7]
	v_lshlrev_b32_e32 v18, 16, v132
	v_and_b32_e32 v19, 0xffff0000, v132
	v_lshlrev_b32_e32 v20, 16, v133
	v_and_b32_e32 v21, 0xffff0000, v133
	ds_write_b128 v186, v[18:21] offset:40960
	s_or_b64 exec, exec, s[40:41]
	v_pk_mul_f32 v[18:19], v[108:109], v[112:113]
	v_pk_mul_f32 v[20:21], v[106:107], v[110:111]
	v_mul_f32_e32 v19, v5, v19
	v_mul_f32_e32 v21, v3, v21
	v_fmac_f32_e32 v21, v2, v20
	v_fmac_f32_e32 v19, v4, v18
	v_add_f32_e32 v18, v21, v19
	v_mov_b32_e32 v20, 0
	s_nop 0
	v_add_f32_dpp v18, v18, v18 row_ror:8 row_mask:0xf bank_mask:0xf bound_ctrl:1
	s_nop 1
	v_add_f32_dpp v18, v18, v18 row_ror:4 row_mask:0xf bank_mask:0xf bound_ctrl:1
	s_nop 1
	v_add_f32_dpp v19, v18, v18 row_ror:2 row_mask:0xf bank_mask:0xf bound_ctrl:1
	s_nop 1
	v_mov_b32_dpp v20, v19 row_ror:1 row_mask:0xf bank_mask:0xf
	s_and_saveexec_b64 s[40:41], s[8:9]
	s_cbranch_execz .LBB0_764
	s_and_b64 vcc, exec, s[4:5]
	s_mov_b64 s[52:53], -1
	s_cbranch_vccnz .LBB0_761
	v_lshl_add_u32 v18, s46, 4, v167
	v_sub_u32_e32 v18, 0x1fdf, v18
	s_mov_b64 s[52:53], 0

.LBB0_778:
	s_waitcnt lgkmcnt(0)
	s_barrier
	s_min_u32 s15, s23, 0x1f9
	s_lshl_b32 s60, s15, 4
	s_addk_i32 s60, 0x60
	s_mul_i32 s60, s60, s56
	s_add_i32 s60, s60, s57
	s_lshl_b32 s61, s60, 12
	s_lshl_b32 s62, s60, 13
	s_add_u32 s64, s12, s61
	s_addc_u32 s65, s13, 0
	global_load_dwordx2 v[144:145], v236, s[64:65]
	s_add_u32 s64, s18, s61
	s_addc_u32 s65, s19, 0
	global_load_dwordx2 v[146:147], v236, s[64:65]
	s_add_u32 s64, s94, s61
	s_addc_u32 s65, s95, 0
	global_load_dwordx2 v[138:139], v236, s[64:65]
	s_add_u32 s64, s28, s62
	s_addc_u32 s65, s29, 0
	global_load_dwordx4 v[22:25], v237, s[64:65]
	s_add_u32 s64, s58, s61
	s_addc_u32 s65, s59, 0
	global_load_dwordx2 v[132:133], v238, s[64:65]
	s_waitcnt vmcnt(22)
	v_pk_add_f32 v[110:111], v[92:93], -1.0 op_sel_hi:[1,0]
	s_add_u32 s64, s30, s62
	s_addc_u32 s65, s31, 0
	global_load_dwordx4 v[18:21], v237, s[64:65]
	v_pk_add_f32 v[112:113], v[90:91], -1.0 op_sel_hi:[1,0]
	v_lshlrev_b32_e32 v190, 16, v154
	v_and_b32_e32 v191, 0xffff0000, v154
	v_lshlrev_b32_e32 v154, 16, v155
	v_and_b32_e32 v155, 0xffff0000, v155
	v_lshlrev_b32_e32 v106, 16, v152
	v_and_b32_e32 v107, 0xffff0000, v152
	v_lshlrev_b32_e32 v108, 16, v153
	v_and_b32_e32 v109, 0xffff0000, v153
	v_pk_fma_f32 v[110:111], v[8:9], v[110:111], 1.0 op_sel_hi:[1,1,0]
	v_pk_fma_f32 v[112:113], v[6:7], v[112:113], 1.0 op_sel_hi:[1,1,0]
	v_pk_mul_f32 v[108:109], v[110:111], v[108:109]
	v_pk_mul_f32 v[106:107], v[112:113], v[106:107]
	v_lshlrev_b32_e32 v110, 16, v150
	v_and_b32_e32 v111, 0xffff0000, v150
	v_lshlrev_b32_e32 v112, 16, v151
	v_and_b32_e32 v113, 0xffff0000, v151
	v_xor_b32_e32 v153, 0x80000000, v155
	v_xor_b32_e32 v152, 0x80000000, v154
	v_xor_b32_e32 v151, 0x80000000, v191
	v_xor_b32_e32 v150, 0x80000000, v190
	v_pk_mul_f32 v[92:93], v[92:93], v[154:155]
	v_pk_mul_f32 v[90:91], v[90:91], v[190:191]
	ds_write_b128 v124, v[150:153] offset:20480
	ds_write_b128 v124, v[94:97] offset:20736
	ds_write_b128 v124, v[90:93] offset:20992
	ds_write_b128 v124, v[106:109] offset:21248
	ds_write_b128 v124, v[110:113] offset:21504
	s_and_saveexec_b64 s[52:53], s[6:7]
	s_cbranch_execz .LBB0_784
	s_waitcnt vmcnt(22)
	v_lshlrev_b32_e32 v90, 16, v148
	v_and_b32_e32 v91, 0xffff0000, v148
	v_lshlrev_b32_e32 v92, 16, v149
	v_and_b32_e32 v93, 0xffff0000, v149
	ds_write_b128 v186, v[90:93] offset:43008

.LBB0_805:
	s_waitcnt lgkmcnt(0)
	s_barrier
	s_min_u32 s15, s23, 0x1f8
	s_lshl_b32 s60, s15, 4
	s_addk_i32 s60, 0x70
	s_mul_i32 s60, s60, s56
	s_add_i32 s60, s60, s57
	s_lshl_b32 s61, s60, 12
	s_lshl_b32 s62, s60, 13
	s_add_u32 s64, s12, s61
	s_addc_u32 s65, s13, 0
	global_load_dwordx2 v[152:153], v236, s[64:65]
	s_add_u32 s64, s18, s61
	s_addc_u32 s65, s19, 0
	global_load_dwordx2 v[154:155], v236, s[64:65]
	s_add_u32 s64, s94, s61
	s_addc_u32 s65, s95, 0
	global_load_dwordx2 v[150:151], v236, s[64:65]
	s_add_u32 s64, s28, s62
	s_addc_u32 s65, s29, 0
	global_load_dwordx4 v[94:97], v237, s[64:65]
	s_add_u32 s64, s58, s61
	s_addc_u32 s65, s59, 0
	global_load_dwordx2 v[148:149], v238, s[64:65]
	s_waitcnt vmcnt(23)
	v_pk_add_f32 v[110:111], v[100:101], -1.0 op_sel_hi:[1,0]
	s_add_u32 s64, s30, s62
	s_addc_u32 s65, s31, 0
	global_load_dwordx4 v[90:93], v237, s[64:65]
	v_pk_add_f32 v[112:113], v[98:99], -1.0 op_sel_hi:[1,0]
	v_lshlrev_b32_e32 v190, 16, v162
	v_and_b32_e32 v191, 0xffff0000, v162
	v_lshlrev_b32_e32 v162, 16, v163
	v_and_b32_e32 v163, 0xffff0000, v163
	v_lshlrev_b32_e32 v106, 16, v160
	v_and_b32_e32 v107, 0xffff0000, v160
	v_lshlrev_b32_e32 v108, 16, v161
	v_and_b32_e32 v109, 0xffff0000, v161
	v_pk_fma_f32 v[110:111], v[8:9], v[110:111], 1.0 op_sel_hi:[1,1,0]
	v_pk_fma_f32 v[112:113], v[6:7], v[112:113], 1.0 op_sel_hi:[1,1,0]
	v_pk_mul_f32 v[108:109], v[110:111], v[108:109]
	v_pk_mul_f32 v[106:107], v[112:113], v[106:107]
	v_lshlrev_b32_e32 v110, 16, v158
	v_and_b32_e32 v111, 0xffff0000, v158
	v_lshlrev_b32_e32 v112, 16, v159
	v_and_b32_e32 v113, 0xffff0000, v159
	v_xor_b32_e32 v161, 0x80000000, v163
	v_xor_b32_e32 v160, 0x80000000, v162
	v_xor_b32_e32 v159, 0x80000000, v191
	v_xor_b32_e32 v158, 0x80000000, v190
	v_pk_mul_f32 v[100:101], v[100:101], v[162:163]
	v_pk_mul_f32 v[98:99], v[98:99], v[190:191]
	ds_write_b128 v124, v[158:161]
	ds_write_b128 v124, v[102:105] offset:256
	ds_write_b128 v124, v[98:101] offset:512
	ds_write_b128 v124, v[106:109] offset:768
	ds_write_b128 v124, v[110:113] offset:1024
	s_and_saveexec_b64 s[42:43], s[6:7]
	v_lshlrev_b32_e32 v98, 16, v156
	v_and_b32_e32 v99, 0xffff0000, v156
	v_lshlrev_b32_e32 v100, 16, v157
	v_and_b32_e32 v101, 0xffff0000, v157
	ds_write_b128 v186, v[98:101] offset:40960
	s_or_b64 exec, exec, s[42:43]
	v_pk_mul_f32 v[98:99], v[108:109], v[112:113]
	v_pk_mul_f32 v[100:101], v[106:107], v[110:111]
	v_mul_f32_e32 v99, v5, v99
	v_mul_f32_e32 v101, v3, v101
	v_fmac_f32_e32 v101, v2, v100
	v_fmac_f32_e32 v99, v4, v98
	v_add_f32_e32 v98, v101, v99
	v_mov_b32_e32 v100, 0
	s_nop 0
	v_add_f32_dpp v98, v98, v98 row_ror:8 row_mask:0xf bank_mask:0xf bound_ctrl:1
	s_nop 1
	v_add_f32_dpp v98, v98, v98 row_ror:4 row_mask:0xf bank_mask:0xf bound_ctrl:1
	s_nop 1
	v_add_f32_dpp v99, v98, v98 row_ror:2 row_mask:0xf bank_mask:0xf bound_ctrl:1
	s_nop 1
	v_mov_b32_dpp v100, v99 row_ror:1 row_mask:0xf bank_mask:0xf
	s_and_saveexec_b64 s[42:43], s[8:9]
	s_cbranch_execz .LBB0_817
	s_and_b64 vcc, exec, s[4:5]
	s_mov_b64 s[52:53], -1
	s_cbranch_vccnz .LBB0_814
	v_lshl_add_u32 v98, s47, 4, v167
	v_sub_u32_e32 v98, 0x1fbf, v98
	s_mov_b64 s[52:53], 0
